# S5 item WT1 stage: complex products rewritten as two packed ops and a select each
# speedup vs baseline: 1.0045x; 1.0010x over previous
.Lssa_514:
	v_add_u32_e32 v8, s82, v4
	v_cmp_gt_u32_e32 vcc, s92, v8
	v_mov_b32_e32 v6, 0
	v_mov_b32_e32 v7, 0
	v_mov_b32_e32 v37, 0
	v_mov_b32_e32 v44, 0
	v_mov_b32_e32 v48, 0
	v_mov_b32_e32 v49, 0
	v_mov_b32_e32 v50, 0
	v_mov_b32_e32 v51, 0
	s_and_saveexec_b64 s[4:5], vcc
	s_cbranch_execz .Lssa_513
	v_add_u32_e32 v6, s82, v65
	v_and_b32_e32 v6, 63, v6
	v_or_b32_e32 v7, v6, v70
	v_lshlrev_b32_e32 v7, 3, v7
	v_xor_b32_e32 v7, 0x1e00, v7
	v_lshl_add_u32 v6, v6, 7, v68
	v_add_u32_e32 v7, 0, v7
	ds_read_b64 v[82:83], v7
	ds_read_b128 v[86:89], v6 offset:8704
	ds_read_b128 v[90:93], v6 offset:8720
	ds_read_b128 v[94:97], v6 offset:8736
	ds_read_b128 v[98:101], v6 offset:8752
	v_cmp_gt_u32_e32 vcc, 64, v8
	s_waitcnt lgkmcnt(3)
	v_pk_mul_f32 v[102:103], v[82:83], v[86:87] op_sel:[1,1] op_sel_hi:[0,1]
	v_pk_fma_f32 v[102:103], v[82:83], v[86:87], v[102:103] op_sel_hi:[1,0,1] neg_lo:[0,0,1]
	v_pk_mul_f32 v[104:105], v[82:83], v[88:89] op_sel:[1,1] op_sel_hi:[0,1]
	v_pk_fma_f32 v[104:105], v[82:83], v[88:89], v[104:105] op_sel_hi:[1,0,1] neg_lo:[0,0,1]
	v_cndmask_b32_e32 v6, v103, v102, vcc
	v_cndmask_b32_e32 v7, v105, v104, vcc
	s_waitcnt lgkmcnt(2)
	v_pk_mul_f32 v[102:103], v[82:83], v[90:91] op_sel:[1,1] op_sel_hi:[0,1]
	v_pk_fma_f32 v[102:103], v[82:83], v[90:91], v[102:103] op_sel_hi:[1,0,1] neg_lo:[0,0,1]
	v_pk_mul_f32 v[104:105], v[82:83], v[92:93] op_sel:[1,1] op_sel_hi:[0,1]
	v_pk_fma_f32 v[104:105], v[82:83], v[92:93], v[104:105] op_sel_hi:[1,0,1] neg_lo:[0,0,1]
	v_cndmask_b32_e32 v37, v103, v102, vcc
	v_cndmask_b32_e32 v44, v105, v104, vcc
	s_waitcnt lgkmcnt(1)
	v_pk_mul_f32 v[102:103], v[82:83], v[94:95] op_sel:[1,1] op_sel_hi:[0,1]
	v_pk_fma_f32 v[102:103], v[82:83], v[94:95], v[102:103] op_sel_hi:[1,0,1] neg_lo:[0,0,1]
	v_pk_mul_f32 v[104:105], v[82:83], v[96:97] op_sel:[1,1] op_sel_hi:[0,1]
	v_pk_fma_f32 v[104:105], v[82:83], v[96:97], v[104:105] op_sel_hi:[1,0,1] neg_lo:[0,0,1]
	v_cndmask_b32_e32 v48, v103, v102, vcc
	v_cndmask_b32_e32 v49, v105, v104, vcc
	s_waitcnt lgkmcnt(0)
	v_pk_mul_f32 v[102:103], v[82:83], v[98:99] op_sel:[1,1] op_sel_hi:[0,1]
	v_pk_fma_f32 v[102:103], v[82:83], v[98:99], v[102:103] op_sel_hi:[1,0,1] neg_lo:[0,0,1]
	v_pk_mul_f32 v[104:105], v[82:83], v[100:101] op_sel:[1,1] op_sel_hi:[0,1]
	v_pk_fma_f32 v[104:105], v[82:83], v[100:101], v[104:105] op_sel_hi:[1,0,1] neg_lo:[0,0,1]
	v_cndmask_b32_e32 v50, v103, v102, vcc
	v_cndmask_b32_e32 v51, v105, v104, vcc
	s_branch .Lssa_513
